# attention: unit-prologue K1 loads issued together with K0/V0 (counted waits), self-max canonicalisations removed from the max->branch chain; on top of store widening + ballot trim
# speedup vs baseline: 1.0040x; 1.0017x over previous
; #define AT_LOADK(t) do { kr0 = *(const v4u*)(kg + (size_t)(t) * 64 * 1024); kr1 = *(const v4u*)(kg + (size_t)(t) * 64 * 1024 + 32 * 1024); } while (0)
; #define AT_LOADV(t) do { vr0 = *(const v4u*)(vg + (t) * 64); vr1 = *(const v4u*)(vg + (size_t)64 * SEQ + (t) * 64); } while (0)
; #define AT_STOREK(bf) do { *(LAS v4u*)(lds + (bf) * AT_KBUF + kso) = kr0; *(LAS v4u*)(lds + (bf) * AT_KBUF + kso + 32 * AT_KSTR * 2) = kr1; } while (0)
; #define AT_STOREV(bf) do { *(LAS v2u*)(lds + (bf) * AT_VBUF + vso) = (v2u){vr0.x, vr0.y}; *(LAS v2u*)(lds + (bf) * AT_VBUF + vso + 8) = (v2u){vr0.z, vr0.w}; \
;         *(LAS v2u*)(lds + (bf) * AT_VBUF + vso + 64 * AT_VSTR * 2) = (v2u){vr1.x, vr1.y}; *(LAS v2u*)(lds + (bf) * AT_VBUF + vso + 64 * AT_VSTR * 2 + 8) = (v2u){vr1.z, vr1.w}; } while (0)
;     ...
;         const int qb = ui == 0 ? g16 : (ui == 1 ? 31 - g16 : (ui == 2 ? 32 + g16 : 63 - g16));
;         const int qw = qb * 128 + 32 * g, NT = 2 * qb + 2, qabs = qw + r;
;         const bf16* qp = Qd + ((size_t)(b * SEQ + qabs)) * 1024 + h * 128 + 64 * mi + 8 * hh;
;         bf16x8_t qf[4];
; #pragma unroll
;         for (int ds = 0; ds < 4; ++ds) qf[ds] = *(const bf16x8_t*)(qp + 16 * ds);
;     ...
;         __syncthreads();
;         AT_LOADK(0); AT_LOADV(0); AT_STOREK(0); AT_STOREV(0); AT_LOADK(1); AT_STOREK(1);
;         __syncthreads();
;         if (isY) __syncthreads();
.LBB0_302:
	s_lshl_b32 s19, s4, 7
	s_add_i32 s18, s19, s42
	v_or_b32_e32 v49, s18, v218
	v_add_u32_e32 v212, s37, v49
	v_ashrrev_i32_e32 v213, 31, v212
	v_lshlrev_b64 v[0:1], 11, v[212:213]
	v_lshl_add_u64 v[0:1], v[180:181], 0, v[0:1]
	global_load_dwordx4 v[144:147], v[0:1], off
	global_load_dwordx4 v[148:151], v[0:1], off offset:32
	global_load_dwordx4 v[152:155], v[0:1], off offset:64
	global_load_dwordx4 v[156:159], v[0:1], off offset:96
	s_waitcnt lgkmcnt(0)
	s_barrier
	global_load_dwordx4 v[0:3], v[176:177], off
	global_load_dwordx4 v[4:7], v[182:183], off
	global_load_dwordx4 v[8:11], v[178:179], off
	global_load_dwordx4 v[12:15], v[184:185], off
	global_load_dwordx4 v[160:163], v[186:187], off
	global_load_dwordx4 v[164:167], v[188:189], off
	s_andn2_b64 vcc, exec, s[24:25]
	s_waitcnt vmcnt(5)
	ds_write_b128 v219, v[0:3]
	s_waitcnt vmcnt(4)
	ds_write_b128 v219, v[4:7] offset:8704
	v_add_u32_e32 v0, 0x8800, v220
	s_waitcnt vmcnt(3)
	ds_write2_b64 v0, v[8:9], v[10:11] offset1:1
	v_add_u32_e32 v0, 0xaa00, v220
	s_waitcnt vmcnt(2)
	ds_write2_b64 v0, v[12:13], v[14:15] offset1:1
	s_waitcnt vmcnt(1)
	ds_write_b128 v219, v[160:163] offset:17408
	s_waitcnt vmcnt(0)
	ds_write_b128 v219, v[164:167] offset:26112
	s_waitcnt lgkmcnt(0)
	s_barrier
	s_cbranch_vccnz .LBB0_304
	s_barrier

.LBB0_466:
	v_max3_f32 v33, v96, v97, v80
	v_max3_f32 v34, v98, v99, v81
	s_mov_b32 s6, 0x40c00000
	v_max3_f32 v33, v33, v82, v83
	v_max3_f32 v34, v34, v102, v103
	v_lshl_add_u64 v[252:253], v[216:217], 0, s[66:67]
	global_load_dwordx4 v[164:167], v[252:253], off
	s_nop 0
	v_max3_f32 v33, v33, v100, v101
	v_max3_f32 v34, v34, v86, v87
	s_nop 0
	v_max3_f32 v33, v33, v84, v85
	v_max3_f32 v34, v34, v106, v107
	s_nop 0
	v_max3_f32 v33, v33, v104, v105
	v_max3_f32 v34, v34, v90, v91
	s_nop 0
	v_max3_f32 v33, v33, v88, v89
	v_max3_f32 v34, v34, v110, v111
	s_nop 0
	v_max3_f32 v33, v33, v108, v109
	v_max3_f32 v34, v34, v94, v95
	s_nop 0
	v_max3_f32 v33, v33, v92, v93
	v_max_f32_e32 v33, v33, v34
	v_mov_b32_e32 v34, v33
	s_nop 1
	v_permlane32_swap_b32_e32 v33, v34
	v_max_f32_e32 v33, v33, v34
	v_sub_f32_e32 v33, v33, v214
	v_cmp_lt_f32_e32 vcc, s6, v33
	s_or_b64 s[6:7], s[40:41], vcc
	s_cbranch_scc0 .LBB0_468
	v_max_f32_e32 v34, v33, v33
	v_max_f32_e32 v34, 0, v34
	v_cndmask_b32_e64 v33, v34, v33, s[40:41]
	v_exp_f32_e64 v34, -v33
	v_add_f32_e32 v214, v214, v33
	v_cndmask_b32_e64 v34, v34, 1.0, s[40:41]
	v_pk_mul_f32 v[78:79], v[78:79], v[34:35] op_sel_hi:[1,0]
	v_pk_mul_f32 v[76:77], v[76:77], v[34:35] op_sel_hi:[1,0]
	v_pk_mul_f32 v[74:75], v[74:75], v[34:35] op_sel_hi:[1,0]
	v_pk_mul_f32 v[72:73], v[72:73], v[34:35] op_sel_hi:[1,0]
	v_pk_mul_f32 v[70:71], v[70:71], v[34:35] op_sel_hi:[1,0]
	v_pk_mul_f32 v[68:69], v[68:69], v[34:35] op_sel_hi:[1,0]
	v_pk_mul_f32 v[66:67], v[66:67], v[34:35] op_sel_hi:[1,0]
	v_pk_mul_f32 v[64:65], v[64:65], v[34:35] op_sel_hi:[1,0]
	v_pk_mul_f32 v[62:63], v[62:63], v[34:35] op_sel_hi:[1,0]
	v_pk_mul_f32 v[60:61], v[60:61], v[34:35] op_sel_hi:[1,0]
	v_pk_mul_f32 v[58:59], v[58:59], v[34:35] op_sel_hi:[1,0]
	v_pk_mul_f32 v[56:57], v[56:57], v[34:35] op_sel_hi:[1,0]
	v_pk_mul_f32 v[54:55], v[54:55], v[34:35] op_sel_hi:[1,0]
	v_pk_mul_f32 v[52:53], v[52:53], v[34:35] op_sel_hi:[1,0]
	v_pk_mul_f32 v[50:51], v[50:51], v[34:35] op_sel_hi:[1,0]
	v_pk_mul_f32 v[48:49], v[48:49], v[34:35] op_sel_hi:[1,0]
	v_pk_mul_f32 v[30:31], v[30:31], v[34:35] op_sel_hi:[1,0]
	v_pk_mul_f32 v[28:29], v[28:29], v[34:35] op_sel_hi:[1,0]
	v_pk_mul_f32 v[26:27], v[26:27], v[34:35] op_sel_hi:[1,0]
	v_pk_mul_f32 v[24:25], v[24:25], v[34:35] op_sel_hi:[1,0]
	v_pk_mul_f32 v[22:23], v[22:23], v[34:35] op_sel_hi:[1,0]
	v_pk_mul_f32 v[20:21], v[20:21], v[34:35] op_sel_hi:[1,0]
	v_pk_mul_f32 v[18:19], v[18:19], v[34:35] op_sel_hi:[1,0]
	v_pk_mul_f32 v[16:17], v[16:17], v[34:35] op_sel_hi:[1,0]
	v_pk_mul_f32 v[14:15], v[14:15], v[34:35] op_sel_hi:[1,0]
	v_pk_mul_f32 v[12:13], v[12:13], v[34:35] op_sel_hi:[1,0]
	v_pk_mul_f32 v[10:11], v[10:11], v[34:35] op_sel_hi:[1,0]
	v_pk_mul_f32 v[8:9], v[8:9], v[34:35] op_sel_hi:[1,0]
	v_pk_mul_f32 v[6:7], v[6:7], v[34:35] op_sel_hi:[1,0]
	v_pk_mul_f32 v[4:5], v[4:5], v[34:35] op_sel_hi:[1,0]
	v_pk_mul_f32 v[2:3], v[2:3], v[34:35] op_sel_hi:[1,0]
	v_pk_mul_f32 v[0:1], v[0:1], v[34:35] op_sel_hi:[1,0]
	v_mul_f32_e32 v250, v250, v34
	s_mov_b64 s[40:41], 0
